# P0 rmsnorm loop software-pipelined: 3 rows of loads in flight per wave
# baseline (speedup 1.0000x reference)
; __device__ __forceinline__ float wave_sum(float v) { return x32_sum(x16_sum(row16_sum(v))); }
; __device__ __forceinline__ void p0_phase(LAS unsigned char* lds, const Args& a, int vcu, int G, int wave, int lane) {
;     ...
;     bf16_t* H = (bf16_t*)((unsigned char*)a.out + DO_H);
;     const f32x4* g4 = (const f32x4*)a.in[I_N1G] + lane;
;     f32x4 g[4];
; #pragma unroll
;     for (int j = 0; j < 4; ++j) g[j] = g4[64 * j];
;     const bool p0al = (NGW == 2048);
;     for (int m0 = gw, k = 0; m0 < MTOK; m0 += NGW, ++k) {
;         const int m = p0al ? 12288 * (gw >> 8) + 256 * (47 - k) + (gw & 255) : m0;
;         const float* xrow = (m < MP) ? a.in[I_XP] + (size_t)m * DM : a.in[I_XS] + (size_t)(m - MP) * DM;
;         const f32x4* xr = (const f32x4*)xrow + lane;
;         f32x4 v[4]; float s = 0.f;
; #pragma unroll
;         for (int j = 0; j < 4; ++j) { v[j] = xr[64 * j]; s += (v[j].x * v[j].x + v[j].y * v[j].y) + (v[j].z * v[j].z + v[j].w * v[j].w); }
;         const float rstd = __builtin_amdgcn_rsqf(wave_sum(s) * (1.f / DM) + EPS);
;         u32x2* o8 = (u32x2*)(H + (size_t)m * DM) + lane;
.LBB0_55:
	s_or_b64 exec, exec, s[4:5]
	s_cmp_gt_i32 s54, 0x17fff
	s_cbranch_scc1 .LBB0_62
	v_lshlrev_b32_e32 v16, 4, v128
	s_waitcnt lgkmcnt(0)
	global_load_dwordx4 v[0:3], v16, s[42:43]
	global_load_dwordx4 v[4:7], v16, s[42:43] offset:1024
	global_load_dwordx4 v[8:11], v16, s[42:43] offset:2048
	global_load_dwordx4 v[12:15], v16, s[42:43] offset:3072
	s_cmpk_eq_i32 s3, 0x100
	s_cselect_b64 s[4:5], -1, 0
	s_lshr_b32 s6, s54, 8
	s_mulk_i32 s6, 0x3000
	s_and_b32 s7, s54, 0xff
	v_mov_b32_e32 v17, 0
	v_lshlrev_b32_e32 v16, 3, v128
	s_or_b32 s6, s6, s7
	v_lshl_add_u64 v[16:17], s[26:27], 0, v[16:17]
	s_add_i32 s22, s6, 0x2f00
	s_mov_b32 s7, 0
	v_lshlrev_b32_e32 v18, 4, v128
	v_mov_b32_e32 v19, 0x358637bd
	s_mov_b32 s72, 0
	s_mov_b32 s71, s54
	s_cmp_lt_i32 s54, 0x18000
	s_cbranch_scc0 .Lp0i_pro0_dup
	s_and_b64 s[10:11], s[4:5], exec
	s_cselect_b32 s71, s22, s54
	s_add_i32 s54, s54, s55
	s_addk_i32 s22, 0xff00
	s_branch .Lp0i_pro0_go
.Lp0i_pro0_dup:
	s_mov_b32 s72, 1
.Lp0i_pro0_go:
	s_mov_b32 s7, 0
	s_cmpk_gt_i32 s71, 0x7fff
	s_cbranch_scc0 .Lp0i_pro0_p
	s_add_i32 s6, s71, 0xffff8000
	s_lshl_b64 s[18:19], s[6:7], 12
	s_add_u32 s18, s38, s18
	s_addc_u32 s19, s39, s19
	s_branch .Lp0i_pro0_ld
.Lp0i_pro0_p:
	s_mov_b32 s6, s71
	s_lshl_b64 s[18:19], s[6:7], 12
	s_add_u32 s18, s36, s18
	s_addc_u32 s19, s37, s19
.Lp0i_pro0_ld:
	global_load_dwordx4 v[20:23], v18, s[18:19]
	global_load_dwordx4 v[24:27], v18, s[18:19] offset:1024
	global_load_dwordx4 v[28:31], v18, s[18:19] offset:2048
	global_load_dwordx4 v[32:35], v18, s[18:19] offset:3072
	s_lshl_b32 s60, s71, 11
	s_mov_b32 s61, 0
	global_load_dwordx4 v[178:181], v18, s[42:43]
	global_load_dwordx4 v[178:181], v18, s[42:43]
	global_load_dwordx4 v[178:181], v18, s[42:43]
	global_load_dwordx4 v[178:181], v18, s[42:43]
	s_cmp_lt_i32 s54, 0x18000
	s_cbranch_scc0 .Lp0i_pro1_dup
	s_and_b64 s[10:11], s[4:5], exec
	s_cselect_b32 s71, s22, s54
	s_add_i32 s54, s54, s55
	s_addk_i32 s22, 0xff00
	s_branch .Lp0i_pro1_go

; __device__ __forceinline__ void p0_phase(LAS unsigned char* lds, const Args& a, int vcu, int G, int wave, int lane) {
;     ...
;     for (int m0 = gw, k = 0; m0 < MTOK; m0 += NGW, ++k) {
;         const int m = p0al ? 12288 * (gw >> 8) + 256 * (47 - k) + (gw & 255) : m0;
;         const float* xrow = (m < MP) ? a.in[I_XP] + (size_t)m * DM : a.in[I_XS] + (size_t)(m - MP) * DM;
;         const f32x4* xr = (const f32x4*)xrow + lane;
;         f32x4 v[4]; float s = 0.f;
.Lp0i_pro1_ld:
	global_load_dwordx4 v[130:133], v18, s[18:19]
	global_load_dwordx4 v[134:137], v18, s[18:19] offset:1024
	global_load_dwordx4 v[138:141], v18, s[18:19] offset:2048
	global_load_dwordx4 v[142:145], v18, s[18:19] offset:3072
	s_lshl_b32 s62, s71, 11
	s_mov_b32 s63, 0
	global_load_dwordx4 v[178:181], v18, s[42:43]
	global_load_dwordx4 v[178:181], v18, s[42:43]
	global_load_dwordx4 v[178:181], v18, s[42:43]
	global_load_dwordx4 v[178:181], v18, s[42:43]
.Lp0_pass:
	s_cmp_lt_i32 s54, 0x18000
	s_cbranch_scc0 .Lp0i_l0_dup
	s_and_b64 s[10:11], s[4:5], exec
	s_cselect_b32 s71, s22, s54
	s_add_i32 s54, s54, s55
	s_addk_i32 s22, 0xff00
	s_branch .Lp0i_l0_go

; __device__ __forceinline__ unsigned cvt_pk_bf16(float lo, float hi) { unsigned r; asm volatile("v_cvt_pk_bf16_f32 %0, %1, %2" : "=v"(r) : "v"(lo), "v"(hi)); return r; }
; __device__ __forceinline__ float wave_sum(float v) { return x32_sum(x16_sum(row16_sum(v))); }
; __device__ __forceinline__ void p0_phase(LAS unsigned char* lds, const Args& a, int vcu, int G, int wave, int lane) {
;     ...
;     for (int m0 = gw, k = 0; m0 < MTOK; m0 += NGW, ++k) {
;         const int m = p0al ? 12288 * (gw >> 8) + 256 * (47 - k) + (gw & 255) : m0;
;         const float* xrow = (m < MP) ? a.in[I_XP] + (size_t)m * DM : a.in[I_XS] + (size_t)(m - MP) * DM;
;         const f32x4* xr = (const f32x4*)xrow + lane;
;         f32x4 v[4]; float s = 0.f;
; #pragma unroll
;         for (int j = 0; j < 4; ++j) { v[j] = xr[64 * j]; s += (v[j].x * v[j].x + v[j].y * v[j].y) + (v[j].z * v[j].z + v[j].w * v[j].w); }
;         const float rstd = __builtin_amdgcn_rsqf(wave_sum(s) * (1.f / DM) + EPS);
;         u32x2* o8 = (u32x2*)(H + (size_t)m * DM) + lane;
; #pragma unroll
;         for (int j = 0; j < 4; ++j) { const f32x4 y = v[j] * rstd * g[j]; u32x2 w; w.x = cvt_pk_bf16(y.x, y.y); w.y = cvt_pk_bf16(y.z, y.w); o8[64 * j] = w; }
;     }
.Lp0i_l0_ld:
	global_load_dwordx4 v[146:149], v18, s[18:19]
	global_load_dwordx4 v[150:153], v18, s[18:19] offset:1024
	global_load_dwordx4 v[154:157], v18, s[18:19] offset:2048
	global_load_dwordx4 v[158:161], v18, s[18:19] offset:3072
	s_lshl_b32 s64, s71, 11
	s_mov_b32 s65, 0
	s_waitcnt vmcnt(16)
	v_mul_f32_e32 v36, v21, v21
	v_mul_f32_e32 v37, v23, v23
	v_mul_f32_e32 v38, v25, v25
	v_mul_f32_e32 v39, v27, v27
	v_mul_f32_e32 v40, v29, v29
	v_mul_f32_e32 v41, v31, v31
	v_fmac_f32_e32 v36, v20, v20
	v_fmac_f32_e32 v37, v22, v22
	v_fmac_f32_e32 v38, v24, v24
	v_fmac_f32_e32 v39, v26, v26
	v_mul_f32_e32 v42, v33, v33
	v_mul_f32_e32 v43, v35, v35
	v_fmac_f32_e32 v40, v28, v28
	v_fmac_f32_e32 v41, v30, v30
	v_add_f32_e32 v36, v36, v37
	v_add_f32_e32 v37, v38, v39
	v_fmac_f32_e32 v42, v32, v32
	v_fmac_f32_e32 v43, v34, v34
	v_add_f32_e32 v38, v40, v41
	v_add_f32_e32 v36, v36, v37
	v_add_f32_e32 v39, v42, v43
	v_add_f32_e32 v36, v36, v38
	v_add_f32_e32 v36, v36, v39
	v_lshl_add_u64 v[38:39], v[16:17], 0, s[60:61]
	s_nop 0
	v_add_f32_dpp v36, v36, v36 quad_perm:[1,0,3,2] row_mask:0xf bank_mask:0xf bound_ctrl:1
	s_nop 1
	v_add_f32_dpp v36, v36, v36 quad_perm:[2,3,0,1] row_mask:0xf bank_mask:0xf bound_ctrl:1
	s_nop 1
	v_add_f32_dpp v36, v36, v36 row_half_mirror row_mask:0xf bank_mask:0xf bound_ctrl:1
	s_nop 1
	v_add_f32_dpp v36, v36, v36 row_ror:8 row_mask:0xf bank_mask:0xf bound_ctrl:1
	v_mov_b32_e32 v37, v36
	s_nop 1
	v_permlane16_swap_b32_e32 v36, v37
	v_add_f32_e32 v36, v36, v37
	v_mov_b32_e32 v37, v36
	s_nop 1
	v_permlane32_swap_b32_e32 v36, v37
	v_add_f32_e32 v36, v36, v37
	v_fmamk_f32 v36, v36, 0x3a800000, v19
	v_rsq_f32_e32 v36, v36
	s_nop 0
	v_pk_mul_f32 v[20:21], v[20:21], v[36:37] op_sel_hi:[1,0]
	v_pk_mul_f32 v[22:23], v[22:23], v[36:37] op_sel_hi:[1,0]
	v_pk_mul_f32 v[20:21], v[0:1], v[20:21]
	v_pk_mul_f32 v[24:25], v[24:25], v[36:37] op_sel_hi:[1,0]
	v_pk_mul_f32 v[26:27], v[26:27], v[36:37] op_sel_hi:[1,0]
	v_pk_mul_f32 v[22:23], v[2:3], v[22:23]
	v_cvt_pk_bf16_f32 v20, v20, v21
	v_pk_mul_f32 v[28:29], v[28:29], v[36:37] op_sel_hi:[1,0]
	v_cvt_pk_bf16_f32 v21, v22, v23
	v_pk_mul_f32 v[30:31], v[30:31], v[36:37] op_sel_hi:[1,0]
	v_pk_mul_f32 v[26:27], v[6:7], v[26:27]
	v_pk_mul_f32 v[24:25], v[4:5], v[24:25]
	global_store_dwordx2 v[38:39], v[20:21], off
	v_cvt_pk_bf16_f32 v20, v24, v25
	v_cvt_pk_bf16_f32 v21, v26, v27
	v_pk_mul_f32 v[32:33], v[32:33], v[36:37] op_sel_hi:[1,0]
	v_pk_mul_f32 v[34:35], v[34:35], v[36:37] op_sel_hi:[1,0]
	v_pk_mul_f32 v[30:31], v[10:11], v[30:31]
	v_pk_mul_f32 v[28:29], v[8:9], v[28:29]
	global_store_dwordx2 v[38:39], v[20:21], off offset:512
	v_cvt_pk_bf16_f32 v20, v28, v29
	v_cvt_pk_bf16_f32 v21, v30, v31
	v_pk_mul_f32 v[34:35], v[14:15], v[34:35]
	v_pk_mul_f32 v[32:33], v[12:13], v[32:33]
	global_store_dwordx2 v[38:39], v[20:21], off offset:1024
	v_cvt_pk_bf16_f32 v20, v32, v33
	v_cvt_pk_bf16_f32 v21, v34, v35
	global_store_dwordx2 v[38:39], v[20:21], off offset:1536
	s_cmp_lt_i32 s54, 0x18000
	s_cbranch_scc0 .Lp0i_l1_dup
	s_and_b64 s[10:11], s[4:5], exec
	s_cselect_b32 s71, s22, s54
	s_add_i32 s54, s54, s55
	s_addk_i32 s22, 0xff00
	s_branch .Lp0i_l1_go

; __device__ __forceinline__ unsigned cvt_pk_bf16(float lo, float hi) { unsigned r; asm volatile("v_cvt_pk_bf16_f32 %0, %1, %2" : "=v"(r) : "v"(lo), "v"(hi)); return r; }
; __device__ __forceinline__ float wave_sum(float v) { return x32_sum(x16_sum(row16_sum(v))); }
; __device__ __forceinline__ void p0_phase(LAS unsigned char* lds, const Args& a, int vcu, int G, int wave, int lane) {
;     ...
;     for (int m0 = gw, k = 0; m0 < MTOK; m0 += NGW, ++k) {
;         const int m = p0al ? 12288 * (gw >> 8) + 256 * (47 - k) + (gw & 255) : m0;
;         const float* xrow = (m < MP) ? a.in[I_XP] + (size_t)m * DM : a.in[I_XS] + (size_t)(m - MP) * DM;
;         const f32x4* xr = (const f32x4*)xrow + lane;
;         f32x4 v[4]; float s = 0.f;
; #pragma unroll
;         for (int j = 0; j < 4; ++j) { v[j] = xr[64 * j]; s += (v[j].x * v[j].x + v[j].y * v[j].y) + (v[j].z * v[j].z + v[j].w * v[j].w); }
;         const float rstd = __builtin_amdgcn_rsqf(wave_sum(s) * (1.f / DM) + EPS);
;         u32x2* o8 = (u32x2*)(H + (size_t)m * DM) + lane;
; #pragma unroll
;         for (int j = 0; j < 4; ++j) { const f32x4 y = v[j] * rstd * g[j]; u32x2 w; w.x = cvt_pk_bf16(y.x, y.y); w.y = cvt_pk_bf16(y.z, y.w); o8[64 * j] = w; }
;     }
.Lp0i_l1_ld:
	global_load_dwordx4 v[20:23], v18, s[18:19]
	global_load_dwordx4 v[24:27], v18, s[18:19] offset:1024
	global_load_dwordx4 v[28:31], v18, s[18:19] offset:2048
	global_load_dwordx4 v[32:35], v18, s[18:19] offset:3072
	s_lshl_b32 s60, s71, 11
	s_mov_b32 s61, 0
	s_mov_b32 s73, s72
	s_waitcnt vmcnt(16)
	v_mul_f32_e32 v36, v131, v131
	v_mul_f32_e32 v37, v133, v133
	v_mul_f32_e32 v38, v135, v135
	v_mul_f32_e32 v39, v137, v137
	v_mul_f32_e32 v40, v139, v139
	v_mul_f32_e32 v41, v141, v141
	v_fmac_f32_e32 v36, v130, v130
	v_fmac_f32_e32 v37, v132, v132
	v_fmac_f32_e32 v38, v134, v134
	v_fmac_f32_e32 v39, v136, v136
	v_mul_f32_e32 v42, v143, v143
	v_mul_f32_e32 v43, v145, v145
	v_fmac_f32_e32 v40, v138, v138
	v_fmac_f32_e32 v41, v140, v140
	v_add_f32_e32 v36, v36, v37
	v_add_f32_e32 v37, v38, v39
	v_fmac_f32_e32 v42, v142, v142
	v_fmac_f32_e32 v43, v144, v144
	v_add_f32_e32 v38, v40, v41
	v_add_f32_e32 v36, v36, v37
	v_add_f32_e32 v39, v42, v43
	v_add_f32_e32 v36, v36, v38
	v_add_f32_e32 v36, v36, v39
	v_lshl_add_u64 v[38:39], v[16:17], 0, s[62:63]
	s_nop 0
	v_add_f32_dpp v36, v36, v36 quad_perm:[1,0,3,2] row_mask:0xf bank_mask:0xf bound_ctrl:1
	s_nop 1
	v_add_f32_dpp v36, v36, v36 quad_perm:[2,3,0,1] row_mask:0xf bank_mask:0xf bound_ctrl:1
	s_nop 1
	v_add_f32_dpp v36, v36, v36 row_half_mirror row_mask:0xf bank_mask:0xf bound_ctrl:1
	s_nop 1
	v_add_f32_dpp v36, v36, v36 row_ror:8 row_mask:0xf bank_mask:0xf bound_ctrl:1
	v_mov_b32_e32 v37, v36
	s_nop 1
	v_permlane16_swap_b32_e32 v36, v37
	v_add_f32_e32 v36, v36, v37
	v_mov_b32_e32 v37, v36
	s_nop 1
	v_permlane32_swap_b32_e32 v36, v37
	v_add_f32_e32 v36, v36, v37
	v_fmamk_f32 v36, v36, 0x3a800000, v19
	v_rsq_f32_e32 v36, v36
	s_nop 0
	v_pk_mul_f32 v[130:131], v[130:131], v[36:37] op_sel_hi:[1,0]
	v_pk_mul_f32 v[132:133], v[132:133], v[36:37] op_sel_hi:[1,0]
	v_pk_mul_f32 v[130:131], v[0:1], v[130:131]
	v_pk_mul_f32 v[134:135], v[134:135], v[36:37] op_sel_hi:[1,0]
	v_pk_mul_f32 v[136:137], v[136:137], v[36:37] op_sel_hi:[1,0]
	v_pk_mul_f32 v[132:133], v[2:3], v[132:133]
	v_cvt_pk_bf16_f32 v130, v130, v131
	v_pk_mul_f32 v[138:139], v[138:139], v[36:37] op_sel_hi:[1,0]
	v_cvt_pk_bf16_f32 v131, v132, v133
	v_pk_mul_f32 v[140:141], v[140:141], v[36:37] op_sel_hi:[1,0]
	v_pk_mul_f32 v[136:137], v[6:7], v[136:137]
	v_pk_mul_f32 v[134:135], v[4:5], v[134:135]
	global_store_dwordx2 v[38:39], v[130:131], off
	v_cvt_pk_bf16_f32 v130, v134, v135
	v_cvt_pk_bf16_f32 v131, v136, v137
	v_pk_mul_f32 v[142:143], v[142:143], v[36:37] op_sel_hi:[1,0]
	v_pk_mul_f32 v[144:145], v[144:145], v[36:37] op_sel_hi:[1,0]
	v_pk_mul_f32 v[140:141], v[10:11], v[140:141]
	v_pk_mul_f32 v[138:139], v[8:9], v[138:139]
	global_store_dwordx2 v[38:39], v[130:131], off offset:512
	v_cvt_pk_bf16_f32 v130, v138, v139
	v_cvt_pk_bf16_f32 v131, v140, v141
	v_pk_mul_f32 v[144:145], v[14:15], v[144:145]
	v_pk_mul_f32 v[142:143], v[12:13], v[142:143]
	global_store_dwordx2 v[38:39], v[130:131], off offset:1024
	v_cvt_pk_bf16_f32 v130, v142, v143
	v_cvt_pk_bf16_f32 v131, v144, v145
	global_store_dwordx2 v[38:39], v[130:131], off offset:1536
	s_cmp_lt_i32 s54, 0x18000
	s_cbranch_scc0 .Lp0i_l2_dup
	s_and_b64 s[10:11], s[4:5], exec
	s_cselect_b32 s71, s22, s54
	s_add_i32 s54, s54, s55
	s_addk_i32 s22, 0xff00
	s_branch .Lp0i_l2_go

; __device__ __forceinline__ unsigned cvt_pk_bf16(float lo, float hi) { unsigned r; asm volatile("v_cvt_pk_bf16_f32 %0, %1, %2" : "=v"(r) : "v"(lo), "v"(hi)); return r; }
; __device__ __forceinline__ float wave_sum(float v) { return x32_sum(x16_sum(row16_sum(v))); }
; __device__ __forceinline__ void p0_phase(LAS unsigned char* lds, const Args& a, int vcu, int G, int wave, int lane) {
;     ...
;     for (int m0 = gw, k = 0; m0 < MTOK; m0 += NGW, ++k) {
;         const int m = p0al ? 12288 * (gw >> 8) + 256 * (47 - k) + (gw & 255) : m0;
;         const float* xrow = (m < MP) ? a.in[I_XP] + (size_t)m * DM : a.in[I_XS] + (size_t)(m - MP) * DM;
;         const f32x4* xr = (const f32x4*)xrow + lane;
;         f32x4 v[4]; float s = 0.f;
; #pragma unroll
;         for (int j = 0; j < 4; ++j) { v[j] = xr[64 * j]; s += (v[j].x * v[j].x + v[j].y * v[j].y) + (v[j].z * v[j].z + v[j].w * v[j].w); }
;         const float rstd = __builtin_amdgcn_rsqf(wave_sum(s) * (1.f / DM) + EPS);
;         u32x2* o8 = (u32x2*)(H + (size_t)m * DM) + lane;
; #pragma unroll
;         for (int j = 0; j < 4; ++j) { const f32x4 y = v[j] * rstd * g[j]; u32x2 w; w.x = cvt_pk_bf16(y.x, y.y); w.y = cvt_pk_bf16(y.z, y.w); o8[64 * j] = w; }
;     }
.Lp0i_l2_ld:
	global_load_dwordx4 v[130:133], v18, s[18:19]
	global_load_dwordx4 v[134:137], v18, s[18:19] offset:1024
	global_load_dwordx4 v[138:141], v18, s[18:19] offset:2048
	global_load_dwordx4 v[142:145], v18, s[18:19] offset:3072
	s_lshl_b32 s62, s71, 11
	s_mov_b32 s63, 0
	s_waitcnt vmcnt(16)
	v_mul_f32_e32 v36, v147, v147
	v_mul_f32_e32 v37, v149, v149
	v_mul_f32_e32 v38, v151, v151
	v_mul_f32_e32 v39, v153, v153
	v_mul_f32_e32 v40, v155, v155
	v_mul_f32_e32 v41, v157, v157
	v_fmac_f32_e32 v36, v146, v146
	v_fmac_f32_e32 v37, v148, v148
	v_fmac_f32_e32 v38, v150, v150
	v_fmac_f32_e32 v39, v152, v152
	v_mul_f32_e32 v42, v159, v159
	v_mul_f32_e32 v43, v161, v161
	v_fmac_f32_e32 v40, v154, v154
	v_fmac_f32_e32 v41, v156, v156
	v_add_f32_e32 v36, v36, v37
	v_add_f32_e32 v37, v38, v39
	v_fmac_f32_e32 v42, v158, v158
	v_fmac_f32_e32 v43, v160, v160
	v_add_f32_e32 v38, v40, v41
	v_add_f32_e32 v36, v36, v37
	v_add_f32_e32 v39, v42, v43
	v_add_f32_e32 v36, v36, v38
	v_add_f32_e32 v36, v36, v39
	v_lshl_add_u64 v[38:39], v[16:17], 0, s[64:65]
	s_nop 0
	v_add_f32_dpp v36, v36, v36 quad_perm:[1,0,3,2] row_mask:0xf bank_mask:0xf bound_ctrl:1
	s_nop 1
	v_add_f32_dpp v36, v36, v36 quad_perm:[2,3,0,1] row_mask:0xf bank_mask:0xf bound_ctrl:1
	s_nop 1
	v_add_f32_dpp v36, v36, v36 row_half_mirror row_mask:0xf bank_mask:0xf bound_ctrl:1
	s_nop 1
	v_add_f32_dpp v36, v36, v36 row_ror:8 row_mask:0xf bank_mask:0xf bound_ctrl:1
	v_mov_b32_e32 v37, v36
	s_nop 1
	v_permlane16_swap_b32_e32 v36, v37
	v_add_f32_e32 v36, v36, v37
	v_mov_b32_e32 v37, v36
	s_nop 1
	v_permlane32_swap_b32_e32 v36, v37
	v_add_f32_e32 v36, v36, v37
	v_fmamk_f32 v36, v36, 0x3a800000, v19
	v_rsq_f32_e32 v36, v36
	s_nop 0
	v_pk_mul_f32 v[146:147], v[146:147], v[36:37] op_sel_hi:[1,0]
	v_pk_mul_f32 v[148:149], v[148:149], v[36:37] op_sel_hi:[1,0]
	v_pk_mul_f32 v[146:147], v[0:1], v[146:147]
	v_pk_mul_f32 v[150:151], v[150:151], v[36:37] op_sel_hi:[1,0]
	v_pk_mul_f32 v[152:153], v[152:153], v[36:37] op_sel_hi:[1,0]
	v_pk_mul_f32 v[148:149], v[2:3], v[148:149]
	v_cvt_pk_bf16_f32 v146, v146, v147
	v_pk_mul_f32 v[154:155], v[154:155], v[36:37] op_sel_hi:[1,0]
	v_cvt_pk_bf16_f32 v147, v148, v149
	v_pk_mul_f32 v[156:157], v[156:157], v[36:37] op_sel_hi:[1,0]
	v_pk_mul_f32 v[152:153], v[6:7], v[152:153]
	v_pk_mul_f32 v[150:151], v[4:5], v[150:151]
	global_store_dwordx2 v[38:39], v[146:147], off
	v_cvt_pk_bf16_f32 v146, v150, v151
	v_cvt_pk_bf16_f32 v147, v152, v153
	v_pk_mul_f32 v[158:159], v[158:159], v[36:37] op_sel_hi:[1,0]
	v_pk_mul_f32 v[160:161], v[160:161], v[36:37] op_sel_hi:[1,0]
	v_pk_mul_f32 v[156:157], v[10:11], v[156:157]
	v_pk_mul_f32 v[154:155], v[8:9], v[154:155]
	global_store_dwordx2 v[38:39], v[146:147], off offset:512
	v_cvt_pk_bf16_f32 v146, v154, v155
	v_cvt_pk_bf16_f32 v147, v156, v157
	v_pk_mul_f32 v[160:161], v[14:15], v[160:161]
	v_pk_mul_f32 v[158:159], v[12:13], v[158:159]
	global_store_dwordx2 v[38:39], v[146:147], off offset:1024
	v_cvt_pk_bf16_f32 v146, v158, v159
	v_cvt_pk_bf16_f32 v147, v160, v161
	global_store_dwordx2 v[38:39], v[146:147], off offset:1536
	s_cmp_eq_u32 s73, 0
	s_cbranch_scc1 .Lp0_pass
	s_waitcnt vmcnt(0)
